# MLA loop: first V fragments of PV prefetched behind the last rope QK steps, PV buffer schedule rotated so its first MFMAs use them
# speedup vs baseline: 1.0036x; 1.0022x over previous
; #define SBAR() __builtin_amdgcn_sched_barrier(0)
; template <bool MLA>
; __device__ __forceinline__ void qkt_fin(f32x16& n0, f32x16& n1, const char* Ks, const char* Krs, const bf16x8* qr, int r32, int hi, const f32x16& cinit,
;                                         f32x16& p1, float alpha, float& l_reg, float ps0, bf16x8& pa2, bf16x8& pa3) {
;     ...
;     for (int s_ = 0; s_ < NSTEP; ++s_) {
;         const bool rope = s_ >= 8; const int d0 = rope ? s_ - 8 : s_; const int cb = (d0 * 16 + hi * 8) * 2;
;         const bf16x8 b0 = rope ? *reinterpret_cast<const bf16x8*>(Krs + KRSWZ(r32, cb)) : *reinterpret_cast<const bf16x8*>(Ks + KSWZ(r32, cb));
;         const bf16x8 b1 = rope ? *reinterpret_cast<const bf16x8*>(Krs + KRSWZ(32 + r32, cb)) : *reinterpret_cast<const bf16x8*>(Ks + KSWZ(32 + r32, cb));
;         if (s_ == 0) { n0 = __builtin_amdgcn_mfma_f32_32x32x16_bf16(b0, qr[0], cinit, 0, 0, 0); n1 = __builtin_amdgcn_mfma_f32_32x32x16_bf16(b1, qr[0], cinit, 0, 0, 0); }
;         else { n0 = __builtin_amdgcn_mfma_f32_32x32x16_bf16(b0, qr[s_], n0, 0, 0, 0); n1 = __builtin_amdgcn_mfma_f32_32x32x16_bf16(b1, qr[s_], n1, 0, 0, 0); }
;         if (s_ < 8) { p1[2 * s_] = __builtin_amdgcn_exp2f(p1[2 * s_]); p1[2 * s_ + 1] = __builtin_amdgcn_exp2f(p1[2 * s_ + 1]); ps += p1[2 * s_] + p1[2 * s_ + 1]; }
;         if (s_ == 4) PK4(p1, 0, pa2);
;         if (MLA && s_ == 8) { LFIN(); PK4(p1, 8, pa3); }
;         SBAR();
; template <int OFF> __device__ __forceinline__ s16x4 tr_read(int vb) {
;     s16x4 r; asm volatile("ds_read_b64_tr_b16 %0, %1 offset:%2" : "=&v"(r) : "v"(vb), "i"(OFF) : "memory"); return r;
; }
; template <int KS> __device__ __forceinline__ void pv_ks(f32x16* o, int vb, bf16x8 pa) {
;     const s16x4 l0 = tr_read<v_rd_off(0, KS, 0)>(vb), h0 = tr_read<v_rd_off(0, KS, 1)>(vb), l1 = tr_read<v_rd_off(1, KS, 0)>(vb), h1 = tr_read<v_rd_off(1, KS, 1)>(vb);
;     const s16x4 l2 = tr_read<v_rd_off(2, KS, 0)>(vb), h2 = tr_read<v_rd_off(2, KS, 1)>(vb), l3 = tr_read<v_rd_off(3, KS, 0)>(vb), h3 = tr_read<v_rd_off(3, KS, 1)>(vb);
;     asm volatile("s_waitcnt lgkmcnt(0)" ::: "memory"); SBAR();
;     ...
;     o[0] = __builtin_amdgcn_mfma_f32_32x32x16_bf16(pa, PK(l0, h0), o[0], 0, 0, 0);
;     o[1] = __builtin_amdgcn_mfma_f32_32x32x16_bf16(pa, PK(l1, h1), o[1], 0, 0, 0);
;     o[2] = __builtin_amdgcn_mfma_f32_32x32x16_bf16(pa, PK(l2, h2), o[2], 0, 0, 0);
.LBB0_459:
	s_lshl_b32 s15, s24, 14
	s_add_i32 s10, s15, 0
	v_add_u32_e32 v100, s10, v224
	ds_read_b128 v[96:99], v100
	ds_read_b128 v[202:205], v100 offset:8192
	v_exp_f32_e32 v188, v80
	v_exp_f32_e32 v189, v81
	s_lshl_b32 s11, s24, 13
	s_waitcnt lgkmcnt(0)
	v_mfma_f32_32x32x16_bf16 v[112:127], v[96:99], v[172:175], v[64:79]
	s_sub_i32 s6, s10, s11
	v_add_f32_e32 v80, v189, v188
	v_add_f32_e32 v80, v80, v200
	v_mfma_f32_32x32x16_bf16 v[96:111], v[202:205], v[172:175], v[64:79]
	v_add_u32_e32 v81, s10, v225
	ds_read_b128 v[200:203], v81
	ds_read_b128 v[242:245], v81 offset:8192
	v_exp_f32_e32 v190, v82
	v_exp_f32_e32 v191, v83
	s_waitcnt lgkmcnt(0)
	v_mfma_f32_32x32x16_bf16 v[112:127], v[200:203], v[168:171], v[112:127]
	v_add_f32_e32 v81, v191, v190
	v_add_f32_e32 v204, v81, v80
	v_mfma_f32_32x32x16_bf16 v[96:111], v[242:245], v[168:171], v[96:111]
	v_add_u32_e32 v200, s10, v226
	ds_read_b128 v[80:83], v200
	ds_read_b128 v[200:203], v200 offset:8192
	v_exp_f32_e32 v205, v84
	v_exp_f32_e32 v206, v85
	s_waitcnt lgkmcnt(0)
	v_mfma_f32_32x32x16_bf16 v[112:127], v[80:83], v[164:167], v[112:127]
	v_add_f32_e32 v80, v206, v205
	v_add_f32_e32 v84, v80, v204
	v_mfma_f32_32x32x16_bf16 v[96:111], v[200:203], v[164:167], v[96:111]
	v_add_u32_e32 v85, s10, v227
	ds_read_b128 v[80:83], v85
	ds_read_b128 v[200:203], v85 offset:8192
	v_exp_f32_e32 v204, v86
	v_exp_f32_e32 v207, v87
	s_waitcnt lgkmcnt(0)
	v_mfma_f32_32x32x16_bf16 v[112:127], v[80:83], v[160:163], v[112:127]
	v_add_f32_e32 v80, v207, v204
	v_add_f32_e32 v208, v80, v84
	v_mfma_f32_32x32x16_bf16 v[96:111], v[200:203], v[160:163], v[96:111]
	v_add_u32_e32 v84, s10, v224
	ds_read_b128 v[80:83], v84 offset:128
	ds_read_b128 v[84:87], v84 offset:8320
	v_exp_f32_e32 v209, v88
	v_exp_f32_e32 v243, v89
	s_waitcnt lgkmcnt(0)
	v_mfma_f32_32x32x16_bf16 v[112:127], v[80:83], v[156:159], v[112:127]
	v_add_f32_e32 v80, v243, v209
	v_add_f32_e32 v88, v80, v208
	v_cvt_pk_bf16_f32 v80, v188, v189
	v_cvt_pk_bf16_f32 v81, v190, v191
	v_cvt_pk_bf16_f32 v82, v205, v206
	v_cvt_pk_bf16_f32 v83, v204, v207
	v_mfma_f32_32x32x16_bf16 v[96:111], v[84:87], v[156:159], v[96:111]
	v_permlane32_swap_b32_e32 v80, v82
	v_permlane32_swap_b32_e32 v81, v83
	v_add_u32_e32 v89, s10, v225
	ds_read_b128 v[84:87], v89 offset:128
	ds_read_b128 v[200:203], v89 offset:8320
	v_exp_f32_e32 v188, v90
	v_exp_f32_e32 v189, v91
	s_waitcnt lgkmcnt(0)
	v_mfma_f32_32x32x16_bf16 v[112:127], v[84:87], v[152:155], v[112:127]
	v_add_f32_e32 v84, v189, v188
	v_add_f32_e32 v190, v84, v88
	v_mfma_f32_32x32x16_bf16 v[96:111], v[200:203], v[152:155], v[96:111]
	v_add_u32_e32 v88, s10, v226
	ds_read_b128 v[84:87], v88 offset:128
	ds_read_b128 v[88:91], v88 offset:8320
	v_exp_f32_e32 v92, v92
	v_exp_f32_e32 v93, v93
	s_waitcnt lgkmcnt(0)
	v_mfma_f32_32x32x16_bf16 v[112:127], v[84:87], v[148:151], v[112:127]
	v_add_f32_e32 v84, v93, v92
	v_add_f32_e32 v190, v84, v190
	v_mfma_f32_32x32x16_bf16 v[96:111], v[88:91], v[148:151], v[96:111]
	v_add_u32_e32 v88, s10, v227
	ds_read_b128 v[84:87], v88 offset:128
	ds_read_b128 v[88:91], v88 offset:8320
	v_exp_f32_e32 v94, v94
	v_exp_f32_e32 v95, v95
	s_waitcnt lgkmcnt(0)
	v_mfma_f32_32x32x16_bf16 v[112:127], v[84:87], v[144:147], v[112:127]
	v_add_f32_e32 v84, v95, v94
	v_add_f32_e32 v241, v84, v190
	v_mfma_f32_32x32x16_bf16 v[96:111], v[88:91], v[144:147], v[96:111]
	v_add_u32_e32 v84, s6, v232
	v_add_u32_e32 v88, s6, v232
	ds_read_b128 v[84:87], v84 offset:49152
	ds_read_b128 v[88:91], v88 offset:53248
	v_mov_b32_e32 v242, v241
	s_nop 1
	v_permlane32_swap_b32_e32 v241, v242
	s_waitcnt lgkmcnt(0)
	v_mfma_f32_32x32x16_bf16 v[112:127], v[84:87], v[140:143], v[112:127]
	v_cvt_pk_bf16_f32 v84, v209, v243
	v_cvt_pk_bf16_f32 v85, v188, v189
	v_cvt_pk_bf16_f32 v86, v92, v93
	v_cvt_pk_bf16_f32 v87, v94, v95
	s_nop 0
	v_permlane32_swap_b32_e32 v84, v86
	v_mfma_f32_32x32x16_bf16 v[96:111], v[88:91], v[140:143], v[96:111]
	v_permlane32_swap_b32_e32 v85, v87
	s_lshl_b32 s21, s21, 14
	v_add_u32_e32 v188, s21, v210
	v_add_u32_e32 v189, s6, v233
	v_add_u32_e32 v190, s6, v234
	ds_read_b128 v[88:91], v189 offset:49152
	ds_read_b128 v[228:231], v189 offset:53248
	ds_read_b128 v[92:95], v190 offset:49152
	ds_read_b128 v[236:239], v190 offset:53248
	v_add_u32_e32 v191, s6, v235
	s_waitcnt lgkmcnt(3)
	v_mfma_f32_32x32x16_bf16 v[112:127], v[88:91], v[136:139], v[112:127]
	s_waitcnt lgkmcnt(2)
	v_mfma_f32_32x32x16_bf16 v[96:111], v[228:231], v[136:139], v[96:111]
	ds_read_b128 v[88:91], v191 offset:49152
	ds_read_b128 v[228:231], v191 offset:53248
	ds_read_b64_tr_b16 v[200:201], v188 offset:0x400
	ds_read_b64_tr_b16 v[202:203], v188 offset:0xc00
	ds_read_b64_tr_b16 v[204:205], v188 offset:0x600
	ds_read_b64_tr_b16 v[206:207], v188 offset:0xe00
	s_waitcnt lgkmcnt(7)
	v_mfma_f32_32x32x16_bf16 v[112:127], v[92:95], v[132:135], v[112:127]
	s_waitcnt lgkmcnt(6)
	v_mfma_f32_32x32x16_bf16 v[96:111], v[236:239], v[132:135], v[96:111]
	s_waitcnt lgkmcnt(5)
	v_mfma_f32_32x32x16_bf16 v[112:127], v[88:91], v[128:131], v[112:127]
	s_waitcnt lgkmcnt(4)
	v_mfma_f32_32x32x16_bf16 v[96:111], v[228:231], v[128:131], v[96:111]
	ds_read_b64_tr_b16 v[88:89], v188 offset:0
	ds_read_b64_tr_b16 v[90:91], v188 offset:0x800
	ds_read_b64_tr_b16 v[92:93], v188 offset:0x200
	ds_read_b64_tr_b16 v[94:95], v188 offset:0xa00
	ds_read_b64_tr_b16 v[228:229], v188 offset:0x1000
	ds_read_b64_tr_b16 v[230:231], v188 offset:0x1800
	ds_read_b64_tr_b16 v[236:237], v188 offset:0x1200
	ds_read_b64_tr_b16 v[238:239], v188 offset:0x1a00
	s_nop 1
	v_max_f32_e32 v189, v113, v113
	v_max_f32_e32 v190, v112, v112
	v_max_f32_e32 v189, v190, v189
	v_max3_f32 v189, v189, v114, v115
	v_max3_f32 v189, v189, v116, v117
	v_max3_f32 v189, v189, v118, v119
	v_max3_f32 v189, v189, v120, v121
	v_max3_f32 v189, v189, v122, v123
	v_max3_f32 v189, v189, v124, v125
	v_max3_f32 v189, v189, v126, v127
	s_waitcnt lgkmcnt(8)
; #define SBAR() __builtin_amdgcn_sched_barrier(0)
; __device__ __forceinline__ void pack_p0(const f32x16& p0, bf16x8& pa0, bf16x8& pa1, float& ps0) {
;     float a = 0.f;
; #pragma unroll
;     for (int r = 0; r < 16; ++r) a += p0[r];
;     ps0 = a; PK4(p0, 0, pa0); PK4(p0, 8, pa1);
; }
; template <int OFF> __device__ __forceinline__ s16x4 tr_read(int vb) {
;     s16x4 r; asm volatile("ds_read_b64_tr_b16 %0, %1 offset:%2" : "=&v"(r) : "v"(vb), "i"(OFF) : "memory"); return r;
; }
; template <int KS> __device__ __forceinline__ void pv_ks(f32x16* o, int vb, bf16x8 pa) {
;     const s16x4 l0 = tr_read<v_rd_off(0, KS, 0)>(vb), h0 = tr_read<v_rd_off(0, KS, 1)>(vb), l1 = tr_read<v_rd_off(1, KS, 0)>(vb), h1 = tr_read<v_rd_off(1, KS, 1)>(vb);
;     const s16x4 l2 = tr_read<v_rd_off(2, KS, 0)>(vb), h2 = tr_read<v_rd_off(2, KS, 1)>(vb), l3 = tr_read<v_rd_off(3, KS, 0)>(vb), h3 = tr_read<v_rd_off(3, KS, 1)>(vb);
;     asm volatile("s_waitcnt lgkmcnt(0)" ::: "memory"); SBAR();
;     ...
;     o[0] = __builtin_amdgcn_mfma_f32_32x32x16_bf16(pa, PK(l0, h0), o[0], 0, 0, 0);
;     o[1] = __builtin_amdgcn_mfma_f32_32x32x16_bf16(pa, PK(l1, h1), o[1], 0, 0, 0);
;     o[2] = __builtin_amdgcn_mfma_f32_32x32x16_bf16(pa, PK(l2, h2), o[2], 0, 0, 0);
;     o[3] = __builtin_amdgcn_mfma_f32_32x32x16_bf16(pa, PK(l3, h3), o[3], 0, 0, 0);
;     ...
; }
; __device__ __forceinline__ void pv_d0(f32x16* o, int vb, bf16x8 pa0, bf16x8 pa1, bf16x8 pa2, bf16x8 pa3) {
;     pv_ks<0>(o, vb, pa0); pv_ks<1>(o, vb, pa1); pv_ks<2>(o, vb, pa2); pv_ks<3>(o, vb, pa3);
	v_mfma_f32_32x32x16_bf16 v[32:47], v[180:183], v[200:203], v[32:47]
	ds_read_b64_tr_b16 v[200:201], v188 offset:0x1400
	ds_read_b64_tr_b16 v[202:203], v188 offset:0x1c00
	v_max3_f32 v189, v189, v96, v97
	v_max3_f32 v189, v189, v98, v99
	v_mfma_f32_32x32x16_bf16 v[16:31], v[180:183], v[204:207], v[16:31]
	ds_read_b64_tr_b16 v[204:205], v188 offset:0x1600
	ds_read_b64_tr_b16 v[206:207], v188 offset:0x1e00
	v_max3_f32 v189, v189, v100, v101
	v_max3_f32 v189, v189, v102, v103
	s_waitcnt lgkmcnt(8)
	v_mfma_f32_32x32x16_bf16 v[0:15], v[180:183], v[88:91], v[0:15]
	v_max3_f32 v189, v189, v104, v105
	v_max3_f32 v189, v189, v106, v107
	v_mfma_f32_32x32x16_bf16 v[48:63], v[180:183], v[92:95], v[48:63]
	ds_read_b64_tr_b16 v[88:89], v188 offset:0x2000
	ds_read_b64_tr_b16 v[90:91], v188 offset:0x2800
	ds_read_b64_tr_b16 v[92:93], v188 offset:0x2200
	ds_read_b64_tr_b16 v[94:95], v188 offset:0x2a00
	v_max3_f32 v189, v189, v108, v109
	v_max3_f32 v189, v189, v110, v111
	v_mov_b32_e32 v190, v189
	s_waitcnt lgkmcnt(4)
	v_mfma_f32_32x32x16_bf16 v[0:15], v[176:179], v[228:231], v[0:15]
	ds_read_b64_tr_b16 v[228:229], v188 offset:0x2400
	ds_read_b64_tr_b16 v[230:231], v188 offset:0x2c00
	v_permlane32_swap_b32_e32 v189, v190
	v_mfma_f32_32x32x16_bf16 v[48:63], v[176:179], v[236:239], v[48:63]
	ds_read_b64_tr_b16 v[236:237], v188 offset:0x2600
	ds_read_b64_tr_b16 v[238:239], v188 offset:0x2e00
	v_max_f32_e32 v190, v190, v190
	v_max_f32_e32 v189, v189, v189
	v_max_f32_e32 v189, v189, v190
	v_mfma_f32_32x32x16_bf16 v[32:47], v[176:179], v[200:203], v[32:47]
	v_cmp_ge_f32_e32 vcc, s90, v189
	s_cmp_eq_u64 vcc, exec
	v_mfma_f32_32x32x16_bf16 v[16:31], v[176:179], v[204:207], v[16:31]
	ds_read_b64_tr_b16 v[200:201], v188 offset:0x3000
	ds_read_b64_tr_b16 v[202:203], v188 offset:0x3800
	ds_read_b64_tr_b16 v[204:205], v188 offset:0x3200
	ds_read_b64_tr_b16 v[206:207], v188 offset:0x3a00
	s_cbranch_scc0 .LBB0_482
	v_mov_b32_e32 v244, 1.0
.LBB0_461:
	v_exp_f32_e32 v112, v112
	v_exp_f32_e32 v113, v113
	v_exp_f32_e32 v114, v114
	v_exp_f32_e32 v115, v115
	s_waitcnt lgkmcnt(4)
	v_mfma_f32_32x32x16_bf16 v[0:15], v[80:83], v[88:91], v[0:15]
	ds_read_b64_tr_b16 v[88:89], v188 offset:0x3400
	ds_read_b64_tr_b16 v[90:91], v188 offset:0x3c00
	v_exp_f32_e32 v116, v116
	v_exp_f32_e32 v117, v117
	v_cvt_pk_bf16_f32 v180, v112, v113
	v_mfma_f32_32x32x16_bf16 v[48:63], v[80:83], v[92:95], v[48:63]
	ds_read_b64_tr_b16 v[92:93], v188 offset:0x3600
	ds_read_b64_tr_b16 v[94:95], v188 offset:0x3e00
	v_exp_f32_e32 v118, v118
	v_exp_f32_e32 v119, v119
	v_cvt_pk_bf16_f32 v181, v114, v115
	v_mfma_f32_32x32x16_bf16 v[32:47], v[80:83], v[228:231], v[32:47]
	v_exp_f32_e32 v120, v120
	v_exp_f32_e32 v121, v121
	v_cvt_pk_bf16_f32 v182, v116, v117
	v_mfma_f32_32x32x16_bf16 v[16:31], v[80:83], v[236:239], v[16:31]
	v_exp_f32_e32 v122, v122
	v_exp_f32_e32 v123, v123
	v_cvt_pk_bf16_f32 v183, v118, v119
	v_add_f32_e32 v191, v113, v112
	s_waitcnt lgkmcnt(0)
	v_mfma_f32_32x32x16_bf16 v[0:15], v[84:87], v[200:203], v[0:15]
	v_exp_f32_e32 v124, v124
	v_exp_f32_e32 v125, v125
	v_permlane32_swap_b32_e32 v180, v182
	v_add_f32_e32 v191, v114, v191
	v_add_f32_e32 v191, v115, v191
	v_mfma_f32_32x32x16_bf16 v[48:63], v[84:87], v[204:207], v[48:63]
	v_exp_f32_e32 v126, v126
	v_exp_f32_e32 v127, v127
	v_permlane32_swap_b32_e32 v181, v183
	v_add_f32_e32 v191, v116, v191
	v_add_f32_e32 v191, v117, v191
	v_mfma_f32_32x32x16_bf16 v[32:47], v[84:87], v[88:91], v[32:47]
	v_cvt_pk_bf16_f32 v176, v120, v121
	v_cvt_pk_bf16_f32 v177, v122, v123
	v_cvt_pk_bf16_f32 v178, v124, v125
	v_add_f32_e32 v191, v118, v191
	v_add_f32_e32 v191, v119, v191
	v_add_f32_e32 v191, v120, v191
	v_mfma_f32_32x32x16_bf16 v[16:31], v[84:87], v[92:95], v[16:31]
	v_cvt_pk_bf16_f32 v179, v126, v127
	v_add_f32_e32 v191, v121, v191
	v_add_f32_e32 v191, v122, v191
	v_add_f32_e32 v191, v123, v191
	v_add_f32_e32 v191, v124, v191
	v_permlane32_swap_b32_e32 v176, v178
	v_add_f32_e32 v191, v125, v191
	v_permlane32_swap_b32_e32 v177, v179
	v_add_f32_e32 v191, v126, v191
	v_add_f32_e32 v84, v127, v191
	v_cmp_gt_f32_e32 vcc, 1.0, v244
	s_cbranch_vccz .LBB0_465
	s_and_saveexec_b64 s[6:7], s[36:37]
	ds_write_b32 v211, v244 offset:128
	s_or_b64 exec, exec, s[6:7]
	s_waitcnt lgkmcnt(0)
	v_add_u32_e32 v124, v193, v184
	ds_read_b128 v[112:115], v124 offset:224
	ds_read_b128 v[116:119], v124 offset:192
	ds_read_b128 v[120:123], v124 offset:160
	ds_read_b128 v[124:127], v124 offset:128
	s_waitcnt lgkmcnt(0)
	v_pk_mul_f32 v[12:13], v[12:13], v[112:113]
	v_pk_mul_f32 v[8:9], v[8:9], v[116:117]
	v_pk_mul_f32 v[4:5], v[4:5], v[120:121]
	v_pk_mul_f32 v[14:15], v[14:15], v[114:115]
	v_pk_mul_f32 v[10:11], v[10:11], v[118:119]
	v_pk_mul_f32 v[6:7], v[6:7], v[122:123]
	v_pk_mul_f32 v[2:3], v[2:3], v[126:127]
	v_pk_mul_f32 v[0:1], v[0:1], v[124:125]
	v_pk_mul_f32 v[60:61], v[60:61], v[112:113]
	v_pk_mul_f32 v[56:57], v[56:57], v[116:117]
	v_pk_mul_f32 v[52:53], v[52:53], v[120:121]
	v_pk_mul_f32 v[62:63], v[62:63], v[114:115]
	v_pk_mul_f32 v[58:59], v[58:59], v[118:119]
	v_pk_mul_f32 v[54:55], v[54:55], v[122:123]
	v_pk_mul_f32 v[50:51], v[50:51], v[126:127]
	v_pk_mul_f32 v[48:49], v[48:49], v[124:125]
	v_pk_mul_f32 v[44:45], v[44:45], v[112:113]
	v_pk_mul_f32 v[40:41], v[40:41], v[116:117]
	v_pk_mul_f32 v[36:37], v[36:37], v[120:121]
	v_pk_mul_f32 v[46:47], v[46:47], v[114:115]
	v_pk_mul_f32 v[42:43], v[42:43], v[118:119]
	v_pk_mul_f32 v[38:39], v[38:39], v[122:123]
	v_pk_mul_f32 v[34:35], v[34:35], v[126:127]
	v_pk_mul_f32 v[32:33], v[32:33], v[124:125]
	v_pk_mul_f32 v[28:29], v[28:29], v[112:113]
	v_pk_mul_f32 v[24:25], v[24:25], v[116:117]
	v_pk_mul_f32 v[20:21], v[20:21], v[120:121]
	v_pk_mul_f32 v[30:31], v[30:31], v[114:115]
	v_pk_mul_f32 v[26:27], v[26:27], v[118:119]
	v_pk_mul_f32 v[22:23], v[22:23], v[122:123]
	v_pk_mul_f32 v[18:19], v[18:19], v[126:127]
	v_pk_mul_f32 v[16:17], v[16:17], v[124:125]

; #define SBAR() __builtin_amdgcn_sched_barrier(0)
; #define LFIN() do { auto rr = __builtin_amdgcn_permlane32_swap(__float_as_uint(ps), __float_as_uint(ps), false, false); \
;     ps = __uint_as_float(rr[0]) + __uint_as_float(rr[1]); l_reg = l_reg * alpha + ps; } while (0)
; template <bool MLA>
; __device__ __forceinline__ void qkt_fin(f32x16& n0, f32x16& n1, const char* Ks, const char* Krs, const bf16x8* qr, int r32, int hi, const f32x16& cinit,
;                                         f32x16& p1, float alpha, float& l_reg, float ps0, bf16x8& pa2, bf16x8& pa3) {
;     constexpr int NSTEP = MLA ? 12 : 8;
;     float ps = ps0;
; #pragma unroll
;     for (int s_ = 0; s_ < NSTEP; ++s_) {
;         const bool rope = s_ >= 8; const int d0 = rope ? s_ - 8 : s_; const int cb = (d0 * 16 + hi * 8) * 2;
;         const bf16x8 b0 = rope ? *reinterpret_cast<const bf16x8*>(Krs + KRSWZ(r32, cb)) : *reinterpret_cast<const bf16x8*>(Ks + KSWZ(r32, cb));
;         const bf16x8 b1 = rope ? *reinterpret_cast<const bf16x8*>(Krs + KRSWZ(32 + r32, cb)) : *reinterpret_cast<const bf16x8*>(Ks + KSWZ(32 + r32, cb));
;         if (s_ == 0) { n0 = __builtin_amdgcn_mfma_f32_32x32x16_bf16(b0, qr[0], cinit, 0, 0, 0); n1 = __builtin_amdgcn_mfma_f32_32x32x16_bf16(b1, qr[0], cinit, 0, 0, 0); }
;         else { n0 = __builtin_amdgcn_mfma_f32_32x32x16_bf16(b0, qr[s_], n0, 0, 0, 0); n1 = __builtin_amdgcn_mfma_f32_32x32x16_bf16(b1, qr[s_], n1, 0, 0, 0); }
;         if (s_ < 8) { p1[2 * s_] = __builtin_amdgcn_exp2f(p1[2 * s_]); p1[2 * s_ + 1] = __builtin_amdgcn_exp2f(p1[2 * s_ + 1]); ps += p1[2 * s_] + p1[2 * s_ + 1]; }
;         if (s_ == 4) PK4(p1, 0, pa2);
;         if (MLA && s_ == 8) { LFIN(); PK4(p1, 8, pa3); }
;         SBAR();
;     }
;     if (!MLA) { LFIN(); PK4(p1, 8, pa3); }
; }
; template <int KS> __device__ __forceinline__ void pv_ks(f32x16* o, int vb, bf16x8 pa) {
;     const s16x4 l0 = tr_read<v_rd_off(0, KS, 0)>(vb), h0 = tr_read<v_rd_off(0, KS, 1)>(vb), l1 = tr_read<v_rd_off(1, KS, 0)>(vb), h1 = tr_read<v_rd_off(1, KS, 1)>(vb);
;     const s16x4 l2 = tr_read<v_rd_off(2, KS, 0)>(vb), h2 = tr_read<v_rd_off(2, KS, 1)>(vb), l3 = tr_read<v_rd_off(3, KS, 0)>(vb), h3 = tr_read<v_rd_off(3, KS, 1)>(vb);
;     asm volatile("s_waitcnt lgkmcnt(0)" ::: "memory"); SBAR();
.LBB0_467:
	s_add_u32 s10, s84, 0x1eec0100
	s_addc_u32 s11, s85, 0
	s_add_i32 s21, s12, s21
	s_mov_b32 m0, s21
	s_nop 0
	global_load_lds_dwordx4 v198, s[10:11]
	s_add_u32 s10, s84, 0x1eee0100
	s_addc_u32 s11, s85, 0
	s_add_i32 m0, s21, 0x2000
	s_nop 0
	global_load_lds_dwordx4 v198, s[10:11]
	s_lshl_b32 s21, s13, 14
	s_add_i32 s24, s21, 0
	v_add_u32_e32 v85, s24, v224
	ds_read_b128 v[80:83], v85
	ds_read_b128 v[246:249], v85 offset:8192
	v_exp_f32_e32 v206, v96
	v_exp_f32_e32 v207, v97
	s_lshl_b32 s25, s13, 13
	s_waitcnt lgkmcnt(0)
	v_mfma_f32_32x32x16_bf16 v[112:127], v[80:83], v[172:175], v[64:79]
	s_sub_i32 s10, s24, s25
	v_add_f32_e32 v80, v207, v206
	v_add_f32_e32 v96, v80, v84
	v_mfma_f32_32x32x16_bf16 v[80:95], v[246:249], v[172:175], v[64:79]
	v_add_u32_e32 v97, s24, v225
	ds_read_b128 v[246:249], v97
	ds_read_b128 v[188:191], v97 offset:8192
	v_exp_f32_e32 v208, v98
	v_exp_f32_e32 v209, v99
	s_waitcnt lgkmcnt(0)
	v_mfma_f32_32x32x16_bf16 v[112:127], v[246:249], v[168:171], v[112:127]
	v_add_f32_e32 v97, v209, v208
	v_add_f32_e32 v243, v97, v96
	v_mfma_f32_32x32x16_bf16 v[80:95], v[188:191], v[168:171], v[80:95]
	v_add_u32_e32 v188, s24, v226
	ds_read_b128 v[96:99], v188
	ds_read_b128 v[188:191], v188 offset:8192
	v_exp_f32_e32 v245, v100
	v_exp_f32_e32 v246, v101
	s_waitcnt lgkmcnt(0)
	v_mfma_f32_32x32x16_bf16 v[112:127], v[96:99], v[164:167], v[112:127]
	v_add_f32_e32 v96, v246, v245
	v_add_f32_e32 v100, v96, v243
	v_mfma_f32_32x32x16_bf16 v[80:95], v[188:191], v[164:167], v[80:95]
	v_add_u32_e32 v101, s24, v227
	ds_read_b128 v[96:99], v101
	ds_read_b128 v[188:191], v101 offset:8192
	v_exp_f32_e32 v243, v102
	v_exp_f32_e32 v247, v103
	s_waitcnt lgkmcnt(0)
	v_mfma_f32_32x32x16_bf16 v[112:127], v[96:99], v[160:163], v[112:127]
	v_add_f32_e32 v96, v247, v243
	v_add_f32_e32 v248, v96, v100
	v_mfma_f32_32x32x16_bf16 v[80:95], v[188:191], v[160:163], v[80:95]
	v_add_u32_e32 v100, s24, v224
	ds_read_b128 v[96:99], v100 offset:128
	ds_read_b128 v[100:103], v100 offset:8320
	v_exp_f32_e32 v249, v104
	v_exp_f32_e32 v186, v105
	s_waitcnt lgkmcnt(0)
	v_mfma_f32_32x32x16_bf16 v[112:127], v[96:99], v[156:159], v[112:127]
	v_add_f32_e32 v96, v186, v249
	v_add_f32_e32 v104, v96, v248
	v_cvt_pk_bf16_f32 v96, v206, v207
	v_cvt_pk_bf16_f32 v97, v208, v209
	v_cvt_pk_bf16_f32 v98, v245, v246
	v_cvt_pk_bf16_f32 v99, v243, v247
	v_mfma_f32_32x32x16_bf16 v[80:95], v[100:103], v[156:159], v[80:95]
	v_permlane32_swap_b32_e32 v96, v98
	v_permlane32_swap_b32_e32 v97, v99
	v_add_u32_e32 v105, s24, v225
	ds_read_b128 v[100:103], v105 offset:128
	ds_read_b128 v[188:191], v105 offset:8320
	v_exp_f32_e32 v206, v106
	v_exp_f32_e32 v207, v107
	s_waitcnt lgkmcnt(0)
	v_mfma_f32_32x32x16_bf16 v[112:127], v[100:103], v[152:155], v[112:127]
	v_add_f32_e32 v100, v207, v206
	v_add_f32_e32 v208, v100, v104
	v_mfma_f32_32x32x16_bf16 v[80:95], v[188:191], v[152:155], v[80:95]
	v_add_u32_e32 v104, s24, v226
	ds_read_b128 v[100:103], v104 offset:128
	ds_read_b128 v[104:107], v104 offset:8320
	v_exp_f32_e32 v188, v108
	v_exp_f32_e32 v189, v109
	s_waitcnt lgkmcnt(0)
	v_mfma_f32_32x32x16_bf16 v[112:127], v[100:103], v[148:151], v[112:127]
	v_add_f32_e32 v100, v189, v188
	v_add_f32_e32 v108, v100, v208
	v_mfma_f32_32x32x16_bf16 v[80:95], v[104:107], v[148:151], v[80:95]
	v_add_u32_e32 v104, s24, v227
	ds_read_b128 v[100:103], v104 offset:128
	ds_read_b128 v[104:107], v104 offset:8320
	v_exp_f32_e32 v110, v110
	v_exp_f32_e32 v111, v111
	s_waitcnt lgkmcnt(0)
	v_mfma_f32_32x32x16_bf16 v[112:127], v[100:103], v[144:147], v[112:127]
	v_add_f32_e32 v100, v111, v110
	v_add_f32_e32 v100, v100, v108
	v_mfma_f32_32x32x16_bf16 v[80:95], v[104:107], v[144:147], v[80:95]
	v_add_u32_e32 v101, s10, v232
	ds_read_b128 v[102:105], v101 offset:49152
	v_add_u32_e32 v101, s10, v232
	ds_read_b128 v[106:109], v101 offset:53248
	v_mov_b32_e32 v101, v100
	s_nop 1
	v_permlane32_swap_b32_e32 v100, v101
	s_waitcnt lgkmcnt(0)
	v_mfma_f32_32x32x16_bf16 v[112:127], v[102:105], v[140:143], v[112:127]
	v_cvt_pk_bf16_f32 v102, v249, v186
	v_cvt_pk_bf16_f32 v103, v206, v207
	v_cvt_pk_bf16_f32 v104, v188, v189
	v_cvt_pk_bf16_f32 v105, v110, v111
	s_nop 0
	v_permlane32_swap_b32_e32 v102, v104
	v_mfma_f32_32x32x16_bf16 v[80:95], v[106:109], v[140:143], v[80:95]
	v_permlane32_swap_b32_e32 v103, v105
	v_add_u32_e32 v110, s15, v210
	v_add_u32_e32 v111, s10, v233
	v_add_u32_e32 v245, s10, v234
	ds_read_b128 v[106:109], v111 offset:49152
	ds_read_b128 v[228:231], v111 offset:53248
	ds_read_b128 v[188:191], v245 offset:49152
	ds_read_b128 v[236:239], v245 offset:53248
	v_add_u32_e32 v186, s10, v235
	s_waitcnt lgkmcnt(3)
	v_mfma_f32_32x32x16_bf16 v[112:127], v[106:109], v[136:139], v[112:127]
	s_waitcnt lgkmcnt(2)
	v_mfma_f32_32x32x16_bf16 v[80:95], v[228:231], v[136:139], v[80:95]
	ds_read_b128 v[106:109], v186 offset:49152
	ds_read_b128 v[228:231], v186 offset:53248
	ds_read_b64_tr_b16 v[246:247], v110 offset:0x400
	ds_read_b64_tr_b16 v[248:249], v110 offset:0xc00
	ds_read_b64_tr_b16 v[206:207], v110 offset:0x600
	ds_read_b64_tr_b16 v[208:209], v110 offset:0xe00
	s_waitcnt lgkmcnt(7)
	v_mfma_f32_32x32x16_bf16 v[112:127], v[188:191], v[132:135], v[112:127]
	s_waitcnt lgkmcnt(6)
	v_mfma_f32_32x32x16_bf16 v[80:95], v[236:239], v[132:135], v[80:95]
	s_waitcnt lgkmcnt(5)
	v_mfma_f32_32x32x16_bf16 v[112:127], v[106:109], v[128:131], v[112:127]
	s_waitcnt lgkmcnt(4)
; template <bool FIRST>
; __device__ __forceinline__ void partialSM_mla(f32x16& p0, f32x16& p1, float& m_reg, f32x16& negm, float& alpha) {
;     constexpr float THRL = THR * LOG2E;
;     float pmax = p0[0];
; #pragma unroll
;     for (int r = 1; r < 16; ++r) pmax = fmaxf(pmax, p0[r]);
; #pragma unroll
;     for (int r = 0; r < 16; ++r) pmax = fmaxf(pmax, p1[r]);
;     { auto rr = __builtin_amdgcn_permlane32_swap(__float_as_uint(pmax), __float_as_uint(pmax), false, false);
;       pmax = fmaxf(__uint_as_float(rr[0]), __uint_as_float(rr[1])); }
;     if (!FIRST && __builtin_expect(__all(pmax <= THRL), 1)) { alpha = 1.f; }
;     else { const float dl = FIRST ? pmax : fmaxf(pmax, 0.f); m_reg += dl; alpha = FIRST ? 1.f : __builtin_amdgcn_exp2f(-dl);
; #pragma unroll
;         for (int r = 0; r < 16; ++r) { p0[r] -= dl; p1[r] -= dl; }
; #pragma unroll
;         for (int r = 0; r < 16; ++r) negm[r] = -m_reg;
;         asm volatile("" : "+v"(negm)); }
; #pragma unroll
;     for (int r = 0; r < 16; ++r) p0[r] = __builtin_amdgcn_exp2f(p0[r]);
; }
; __device__ __forceinline__ void pack_p0(const f32x16& p0, bf16x8& pa0, bf16x8& pa1, float& ps0) {
;     float a = 0.f;
; #pragma unroll
;     for (int r = 0; r < 16; ++r) a += p0[r];
;     ps0 = a; PK4(p0, 0, pa0); PK4(p0, 8, pa1);
; }
; __device__ __forceinline__ void fin_p1(f32x16& p1, float alpha, float& l_reg, float ps0, bf16x8& pa2, bf16x8& pa3) {
;     float ps = ps0;
; #pragma unroll
;     for (int r = 0; r < 16; ++r) { p1[r] = __builtin_amdgcn_exp2f(p1[r]); ps += p1[r]; }
;     LFIN(); PK4(p1, 0, pa2); PK4(p1, 8, pa3);
; }
; template <bool MLA>
; __device__ __forceinline__ void qkt_fin(f32x16& n0, f32x16& n1, const char* Ks, const char* Krs, const bf16x8* qr, int r32, int hi, const f32x16& cinit,
;                                         f32x16& p1, float alpha, float& l_reg, float ps0, bf16x8& pa2, bf16x8& pa3) {
;     constexpr int NSTEP = MLA ? 12 : 8;
;     float ps = ps0;
; #pragma unroll
;     for (int s_ = 0; s_ < NSTEP; ++s_) {
;         const bool rope = s_ >= 8; const int d0 = rope ? s_ - 8 : s_; const int cb = (d0 * 16 + hi * 8) * 2;
;         const bf16x8 b0 = rope ? *reinterpret_cast<const bf16x8*>(Krs + KRSWZ(r32, cb)) : *reinterpret_cast<const bf16x8*>(Ks + KSWZ(r32, cb));
	v_mfma_f32_32x32x16_bf16 v[80:95], v[228:231], v[128:131], v[80:95]
	ds_read_b64_tr_b16 v[106:107], v110 offset:0
	ds_read_b64_tr_b16 v[108:109], v110 offset:0x800
	ds_read_b64_tr_b16 v[188:189], v110 offset:0x200
	ds_read_b64_tr_b16 v[190:191], v110 offset:0xa00
	ds_read_b64_tr_b16 v[228:229], v110 offset:0x1000
	ds_read_b64_tr_b16 v[230:231], v110 offset:0x1800
	ds_read_b64_tr_b16 v[236:237], v110 offset:0x1200
	ds_read_b64_tr_b16 v[238:239], v110 offset:0x1a00
	s_nop 1
	v_max_f32_e32 v111, v113, v113
	v_max_f32_e32 v245, v112, v112
	v_max_f32_e32 v111, v245, v111
	v_max3_f32 v111, v111, v114, v115
	v_max3_f32 v111, v111, v116, v117
	v_max3_f32 v111, v111, v118, v119
	v_max3_f32 v111, v111, v120, v121
	v_max3_f32 v111, v111, v122, v123
	v_max3_f32 v111, v111, v124, v125
	v_max3_f32 v111, v111, v126, v127
	s_waitcnt lgkmcnt(8)
	v_mfma_f32_32x32x16_bf16 v[32:47], v[180:183], v[246:249], v[32:47]
	ds_read_b64_tr_b16 v[246:247], v110 offset:0x1400
	ds_read_b64_tr_b16 v[248:249], v110 offset:0x1c00
	v_max3_f32 v111, v111, v80, v81
	v_max3_f32 v111, v111, v82, v83
	v_mfma_f32_32x32x16_bf16 v[16:31], v[180:183], v[206:209], v[16:31]
	ds_read_b64_tr_b16 v[206:207], v110 offset:0x1600
	ds_read_b64_tr_b16 v[208:209], v110 offset:0x1e00
	v_max3_f32 v111, v111, v84, v85
	v_max3_f32 v111, v111, v86, v87
	s_waitcnt lgkmcnt(8)
	v_mfma_f32_32x32x16_bf16 v[0:15], v[180:183], v[106:109], v[0:15]
	v_max3_f32 v111, v111, v88, v89
	v_max3_f32 v111, v111, v90, v91
	v_mfma_f32_32x32x16_bf16 v[48:63], v[180:183], v[188:191], v[48:63]
	ds_read_b64_tr_b16 v[106:107], v110 offset:0x2000
	ds_read_b64_tr_b16 v[108:109], v110 offset:0x2800
	ds_read_b64_tr_b16 v[188:189], v110 offset:0x2200
	ds_read_b64_tr_b16 v[190:191], v110 offset:0x2a00
	v_max3_f32 v111, v111, v92, v93
	v_max3_f32 v111, v111, v94, v95
	v_mov_b32_e32 v245, v111
	s_waitcnt lgkmcnt(4)
	v_mfma_f32_32x32x16_bf16 v[0:15], v[176:179], v[228:231], v[0:15]
	ds_read_b64_tr_b16 v[228:229], v110 offset:0x2400
	ds_read_b64_tr_b16 v[230:231], v110 offset:0x2c00
	v_permlane32_swap_b32_e32 v111, v245
	v_mfma_f32_32x32x16_bf16 v[48:63], v[176:179], v[236:239], v[48:63]
	ds_read_b64_tr_b16 v[236:237], v110 offset:0x2600
	ds_read_b64_tr_b16 v[238:239], v110 offset:0x2e00
	v_max_f32_e32 v245, v245, v245
	v_max_f32_e32 v111, v111, v111
	v_max_f32_e32 v111, v111, v245
	v_mfma_f32_32x32x16_bf16 v[32:47], v[176:179], v[246:249], v[32:47]
	v_cmp_ge_f32_e32 vcc, s90, v111
	s_cmp_eq_u64 vcc, exec
	v_mov_b32_e32 v243, 1.0
	v_mfma_f32_32x32x16_bf16 v[16:31], v[176:179], v[206:209], v[16:31]
	ds_read_b64_tr_b16 v[246:247], v110 offset:0x3000
	ds_read_b64_tr_b16 v[248:249], v110 offset:0x3800
	ds_read_b64_tr_b16 v[206:207], v110 offset:0x3200
	ds_read_b64_tr_b16 v[208:209], v110 offset:0x3a00
	s_cbranch_scc0 .LBB0_483
.LBB0_468:
	v_exp_f32_e32 v112, v112
	v_exp_f32_e32 v113, v113
	v_exp_f32_e32 v114, v114
	v_exp_f32_e32 v115, v115
	s_waitcnt lgkmcnt(4)
	v_mfma_f32_32x32x16_bf16 v[0:15], v[96:99], v[106:109], v[0:15]
	ds_read_b64_tr_b16 v[106:107], v110 offset:0x3400
	ds_read_b64_tr_b16 v[108:109], v110 offset:0x3c00
	v_exp_f32_e32 v116, v116
	v_exp_f32_e32 v117, v117
	v_cvt_pk_bf16_f32 v180, v112, v113
	v_mfma_f32_32x32x16_bf16 v[48:63], v[96:99], v[188:191], v[48:63]
	ds_read_b64_tr_b16 v[188:189], v110 offset:0x3600
	ds_read_b64_tr_b16 v[190:191], v110 offset:0x3e00
	v_exp_f32_e32 v118, v118
	v_exp_f32_e32 v119, v119
	v_cvt_pk_bf16_f32 v181, v114, v115
	v_mfma_f32_32x32x16_bf16 v[32:47], v[96:99], v[228:231], v[32:47]
	v_exp_f32_e32 v120, v120
	v_exp_f32_e32 v121, v121
	v_cvt_pk_bf16_f32 v182, v116, v117
	v_mfma_f32_32x32x16_bf16 v[16:31], v[96:99], v[236:239], v[16:31]
	v_exp_f32_e32 v122, v122
	v_exp_f32_e32 v123, v123
	v_cvt_pk_bf16_f32 v183, v118, v119
	v_add_f32_e32 v186, v113, v112
	s_waitcnt lgkmcnt(0)
	v_mfma_f32_32x32x16_bf16 v[0:15], v[102:105], v[246:249], v[0:15]
	v_exp_f32_e32 v124, v124
	v_exp_f32_e32 v125, v125
	v_permlane32_swap_b32_e32 v180, v182
	v_add_f32_e32 v186, v114, v186
	v_add_f32_e32 v186, v115, v186
	v_mfma_f32_32x32x16_bf16 v[48:63], v[102:105], v[206:209], v[48:63]
	v_exp_f32_e32 v126, v126
	v_exp_f32_e32 v127, v127
	v_permlane32_swap_b32_e32 v181, v183
	v_add_f32_e32 v186, v116, v186
	v_add_f32_e32 v186, v117, v186
	v_mfma_f32_32x32x16_bf16 v[32:47], v[102:105], v[106:109], v[32:47]
	v_cvt_pk_bf16_f32 v176, v120, v121
	v_cvt_pk_bf16_f32 v177, v122, v123
	v_cvt_pk_bf16_f32 v178, v124, v125
	v_add_f32_e32 v186, v118, v186
	v_add_f32_e32 v186, v119, v186
	v_add_f32_e32 v186, v120, v186
	v_mfma_f32_32x32x16_bf16 v[16:31], v[102:105], v[188:191], v[16:31]
	v_cvt_pk_bf16_f32 v179, v126, v127
	v_add_f32_e32 v186, v121, v186
	v_add_f32_e32 v186, v122, v186
	v_add_f32_e32 v186, v123, v186
	v_add_f32_e32 v186, v124, v186
	v_permlane32_swap_b32_e32 v176, v178
	v_add_f32_e32 v186, v125, v186
	v_permlane32_swap_b32_e32 v177, v179
	v_add_f32_e32 v186, v126, v186
	v_add_f32_e32 v186, v127, v186
	v_cmp_gt_f32_e32 vcc, 1.0, v243
	s_cbranch_vccz .LBB0_472
	s_and_saveexec_b64 s[10:11], s[36:37]
	ds_write_b32 v211, v243 offset:128
	s_or_b64 exec, exec, s[10:11]
	s_waitcnt lgkmcnt(0)
	v_add_u32_e32 v126, v193, v184
	ds_read_b128 v[114:117], v126 offset:224
	ds_read_b128 v[118:121], v126 offset:192
	ds_read_b128 v[122:125], v126 offset:160
	ds_read_b128 v[188:191], v126 offset:128
	s_waitcnt lgkmcnt(0)
	v_pk_mul_f32 v[12:13], v[12:13], v[114:115]
	v_pk_mul_f32 v[8:9], v[8:9], v[118:119]
	v_pk_mul_f32 v[4:5], v[4:5], v[122:123]
	v_pk_mul_f32 v[14:15], v[14:15], v[116:117]
	v_pk_mul_f32 v[10:11], v[10:11], v[120:121]
	v_pk_mul_f32 v[6:7], v[6:7], v[124:125]
	v_pk_mul_f32 v[2:3], v[2:3], v[190:191]
	v_pk_mul_f32 v[0:1], v[0:1], v[188:189]
	v_pk_mul_f32 v[60:61], v[60:61], v[114:115]
	v_pk_mul_f32 v[56:57], v[56:57], v[118:119]
	v_pk_mul_f32 v[52:53], v[52:53], v[122:123]
	v_pk_mul_f32 v[62:63], v[62:63], v[116:117]
	v_pk_mul_f32 v[58:59], v[58:59], v[120:121]
	v_pk_mul_f32 v[54:55], v[54:55], v[124:125]
	v_pk_mul_f32 v[50:51], v[50:51], v[190:191]
	v_pk_mul_f32 v[48:49], v[48:49], v[188:189]
	v_pk_mul_f32 v[44:45], v[44:45], v[114:115]
	v_pk_mul_f32 v[40:41], v[40:41], v[118:119]
	v_pk_mul_f32 v[36:37], v[36:37], v[122:123]
	v_pk_mul_f32 v[46:47], v[46:47], v[116:117]
	v_pk_mul_f32 v[42:43], v[42:43], v[120:121]
	v_pk_mul_f32 v[38:39], v[38:39], v[124:125]
	v_pk_mul_f32 v[34:35], v[34:35], v[190:191]
	v_pk_mul_f32 v[32:33], v[32:33], v[188:189]
	v_pk_mul_f32 v[28:29], v[28:29], v[114:115]
	v_pk_mul_f32 v[24:25], v[24:25], v[118:119]
	v_pk_mul_f32 v[20:21], v[20:21], v[122:123]
	v_pk_mul_f32 v[30:31], v[30:31], v[116:117]
	v_pk_mul_f32 v[26:27], v[26:27], v[120:121]
	v_pk_mul_f32 v[22:23], v[22:23], v[124:125]
	v_pk_mul_f32 v[18:19], v[18:19], v[190:191]
	v_pk_mul_f32 v[16:17], v[16:17], v[188:189]
